# plus: norm2 slab loads issued together, XCC rank check loads issued together, mix3 HGRN q.S fragment reads and RMS partial reads batched with counted waits
# speedup vs baseline: 1.0113x; 1.0113x over previous
.LBB0_144:
	s_or_b64 exec, exec, s[0:1]
	v_readlane_b32 s0, v252, 0
	s_and_b32 s0, s0, 7
	s_cmp_lg_u32 s0, 0
	s_waitcnt lgkmcnt(0)
	s_barrier
	s_cbranch_scc1 .LBB0_157
	s_mov_b64 s[0:1], exec
	v_readlane_b32 s4, v252, 5
	v_readlane_b32 s5, v252, 6
	s_and_b64 s[4:5], s[0:1], s[4:5]
	s_mov_b64 exec, s[4:5]
	s_cbranch_execz .LBB0_156
	s_waitcnt vmcnt(23)
	v_mov_b32_e32 v2, 0x3000
	global_load_dword v3, v2, s[26:27] sc1
	global_load_dword v4, v2, s[26:27] offset:256 sc1
	global_load_dword v5, v2, s[26:27] offset:512 sc1
	global_load_dword v6, v2, s[26:27] offset:768 sc1
	global_load_dword v7, v2, s[26:27] offset:1024 sc1
	global_load_dword v8, v2, s[26:27] offset:1280 sc1
	global_load_dword v9, v2, s[26:27] offset:1536 sc1
	global_load_dword v10, v2, s[26:27] offset:1792 sc1
	v_readlane_b32 s4, v252, 0
	s_ashr_i32 s4, s4, 3
	s_waitcnt vmcnt(0)
	v_mov_b32_e32 v1, s60
	v_cmp_ne_u32_e32 vcc, s4, v3
	s_nop 0
	s_cbranch_vccnz .LBB0_155
	v_cmp_ne_u32_e32 vcc, s4, v4
	s_nop 0
	s_cbranch_vccnz .LBB0_155
	v_cmp_ne_u32_e32 vcc, s4, v5
	s_nop 0
	s_cbranch_vccnz .LBB0_155
	v_cmp_ne_u32_e32 vcc, s4, v6
	s_nop 0
	s_cbranch_vccnz .LBB0_155
	v_cmp_ne_u32_e32 vcc, s4, v7
	s_nop 0
	s_cbranch_vccnz .LBB0_155
	v_cmp_ne_u32_e32 vcc, s4, v8
	s_nop 0
	s_cbranch_vccnz .LBB0_155
	v_cmp_ne_u32_e32 vcc, s4, v9
	s_nop 0
	s_cbranch_vccnz .LBB0_155
	v_cmp_ne_u32_e32 vcc, s4, v10
	s_nop 0
	s_cbranch_vccnz .LBB0_155
	s_add_i32 s4, 0, 0x24044
	v_mov_b32_e32 v1, s4
	s_add_i32 s4, 0, 0x24040
	ds_read_b32 v1, v1
	v_mov_b32_e32 v2, s4
	ds_read_b32 v2, v2
	s_waitcnt lgkmcnt(1)
	v_lshlrev_b32_e32 v1, 3, v1
	s_waitcnt lgkmcnt(0)
	v_add_u32_e32 v1, v1, v2

.LBB0_1103:
	s_or_b64 exec, exec, s[16:17]
	s_waitcnt lgkmcnt(0)
	s_barrier
	v_add_u32_e32 v33, 0x400, v212
	ds_read2_b32 v[2:3], v212 offset0:0 offset1:64
	ds_read2_b32 v[4:5], v212 offset0:128 offset1:192
	ds_read2_b32 v[6:7], v33 offset0:0 offset1:64
	ds_read2_b32 v[8:9], v33 offset0:128 offset1:192
	ds_read2_b32 v[10:11], v212 offset0:16 offset1:80
	ds_read2_b32 v[12:13], v212 offset0:144 offset1:208
	ds_read2_b32 v[14:15], v33 offset0:16 offset1:80
	ds_read2_b32 v[16:17], v33 offset0:144 offset1:208
	ds_read2_b32 v[18:19], v212 offset0:32 offset1:96
	ds_read2_b32 v[20:21], v212 offset0:160 offset1:224
	ds_read2_b32 v[22:23], v33 offset0:32 offset1:96
	ds_read2_b32 v[24:25], v33 offset0:160 offset1:224
	ds_read2_b32 v[26:27], v212 offset0:48 offset1:112
	ds_read2_b32 v[28:29], v212 offset0:176 offset1:240
	ds_read2_b32 v[30:31], v33 offset0:48 offset1:112
	ds_read2_b32 v[32:33], v33 offset0:176 offset1:240
	s_add_i32 s14, s14, 64
	s_cmp_lg_u32 s70, s71
	s_waitcnt lgkmcnt(15)
	v_add_f32_e32 v176, 0, v2
	v_add_f32_e32 v178, v176, v3
	s_waitcnt lgkmcnt(14)
	v_add_f32_e32 v176, v178, v4
	v_add_f32_e32 v178, v176, v5
	s_waitcnt lgkmcnt(13)
	v_add_f32_e32 v176, v178, v6
	v_add_f32_e32 v178, v176, v7
	s_waitcnt lgkmcnt(12)
	v_add_f32_e32 v176, v178, v8
	v_add_f32_e32 v176, v176, v9
	v_fmamk_f32 v176, v176, 0x3c000000, v249
	v_rsq_f32_e32 v176, v176
	s_nop 0
	v_pk_mul_f32 v[172:173], v[172:173], v[176:177] op_sel_hi:[1,0]
	v_pk_mul_f32 v[174:175], v[174:175], v[176:177] op_sel_hi:[1,0]
	v_pk_mul_f32 v[172:173], v[68:69], v[172:173]
	s_waitcnt vmcnt(3)
	v_lshlrev_b32_e32 v176, 16, v210
	v_mul_f32_e32 v172, v172, v176
	v_and_b32_e32 v176, 0xffff0000, v210
	v_mul_f32_e32 v173, v173, v176
	v_pk_mul_f32 v[174:175], v[70:71], v[174:175]
	v_cvt_pk_bf16_f32 v172, v172, v173
	v_lshlrev_b32_e32 v173, 16, v211
	v_mul_f32_e32 v173, v174, v173
	v_and_b32_e32 v174, 0xffff0000, v211
	v_mul_f32_e32 v174, v175, v174
	v_cvt_pk_bf16_f32 v173, v173, v174
	v_lshlrev_b64 v[174:175], 12, v[208:209]
	v_lshl_add_u64 v[174:175], v[194:195], 0, v[174:175]
	global_store_dwordx2 v[174:175], v[172:173], off
	v_add_u32_e32 v175, 64, v212
	s_waitcnt lgkmcnt(11)
	v_add_f32_e32 v172, 0, v10
	v_add_f32_e32 v174, v172, v11
	s_waitcnt lgkmcnt(10)
	v_add_f32_e32 v172, v174, v12
	v_add_f32_e32 v174, v172, v13
	s_waitcnt lgkmcnt(9)
	v_add_f32_e32 v172, v174, v14
	v_add_f32_e32 v174, v172, v15
	s_waitcnt lgkmcnt(8)
	v_add_f32_e32 v172, v174, v16
	v_add_f32_e32 v172, v172, v17
	v_fmamk_f32 v172, v172, 0x3c000000, v249
	v_rsq_f32_e32 v172, v172
	s_nop 0
	v_pk_mul_f32 v[168:169], v[168:169], v[172:173] op_sel_hi:[1,0]
	v_pk_mul_f32 v[170:171], v[170:171], v[172:173] op_sel_hi:[1,0]
	v_pk_mul_f32 v[168:169], v[68:69], v[168:169]
	s_waitcnt vmcnt(3)
	v_lshlrev_b32_e32 v172, 16, v206
	v_mul_f32_e32 v168, v168, v172
	v_and_b32_e32 v172, 0xffff0000, v206
	v_mul_f32_e32 v169, v169, v172
	v_pk_mul_f32 v[170:171], v[70:71], v[170:171]
	v_cvt_pk_bf16_f32 v168, v168, v169
	v_lshlrev_b32_e32 v169, 16, v207
	v_mul_f32_e32 v169, v170, v169
	v_and_b32_e32 v170, 0xffff0000, v207
	v_mul_f32_e32 v170, v171, v170
	v_cvt_pk_bf16_f32 v169, v169, v170
	v_lshlrev_b64 v[170:171], 12, v[204:205]
	v_lshl_add_u64 v[170:171], v[194:195], 0, v[170:171]
	global_store_dwordx2 v[170:171], v[168:169], off
	v_add_u32_e32 v171, 0x80, v212
	s_waitcnt lgkmcnt(7)
	v_add_f32_e32 v168, 0, v18
	v_add_f32_e32 v170, v168, v19
	s_waitcnt lgkmcnt(6)
	v_add_f32_e32 v168, v170, v20
	v_add_f32_e32 v170, v168, v21
	s_waitcnt lgkmcnt(5)
	v_add_f32_e32 v168, v170, v22
	v_add_f32_e32 v170, v168, v23
	s_waitcnt lgkmcnt(4)
	v_add_f32_e32 v168, v170, v24
	v_add_f32_e32 v168, v168, v25
	v_fmamk_f32 v168, v168, 0x3c000000, v249
	v_rsq_f32_e32 v168, v168
	s_nop 0
	v_pk_mul_f32 v[164:165], v[164:165], v[168:169] op_sel_hi:[1,0]
	v_pk_mul_f32 v[166:167], v[166:167], v[168:169] op_sel_hi:[1,0]
	v_pk_mul_f32 v[164:165], v[68:69], v[164:165]
	s_waitcnt vmcnt(3)
	v_lshlrev_b32_e32 v168, 16, v202
	v_mul_f32_e32 v164, v164, v168
	v_and_b32_e32 v168, 0xffff0000, v202
	v_mul_f32_e32 v165, v165, v168
	v_pk_mul_f32 v[166:167], v[70:71], v[166:167]
	v_cvt_pk_bf16_f32 v164, v164, v165
	v_lshlrev_b32_e32 v165, 16, v203
	v_mul_f32_e32 v165, v166, v165
	v_and_b32_e32 v166, 0xffff0000, v203
	v_mul_f32_e32 v166, v167, v166
	v_cvt_pk_bf16_f32 v165, v165, v166
	v_lshlrev_b64 v[166:167], 12, v[200:201]
	v_lshl_add_u64 v[166:167], v[194:195], 0, v[166:167]
	global_store_dwordx2 v[166:167], v[164:165], off
	v_add_u32_e32 v167, 0xc0, v212
	s_waitcnt lgkmcnt(3)
	v_add_f32_e32 v164, 0, v26
	v_add_f32_e32 v166, v164, v27
	s_waitcnt lgkmcnt(2)
	v_add_f32_e32 v164, v166, v28
	v_add_f32_e32 v166, v164, v29
	s_waitcnt lgkmcnt(1)
	v_add_f32_e32 v164, v166, v30
	v_add_f32_e32 v166, v164, v31
	s_waitcnt lgkmcnt(0)
	v_add_f32_e32 v164, v166, v32
	v_add_f32_e32 v164, v164, v33
	v_fmamk_f32 v164, v164, 0x3c000000, v249
	v_rsq_f32_e32 v164, v164
	s_nop 0
	v_pk_mul_f32 v[160:161], v[160:161], v[164:165] op_sel_hi:[1,0]
	v_pk_mul_f32 v[162:163], v[162:163], v[164:165] op_sel_hi:[1,0]
	v_pk_mul_f32 v[160:161], v[68:69], v[160:161]
	s_waitcnt vmcnt(3)
	v_lshlrev_b32_e32 v164, 16, v198
	v_mul_f32_e32 v160, v160, v164
	v_and_b32_e32 v164, 0xffff0000, v198
	v_mul_f32_e32 v161, v161, v164
	v_pk_mul_f32 v[162:163], v[70:71], v[162:163]
	v_cvt_pk_bf16_f32 v160, v160, v161
	v_lshlrev_b32_e32 v161, 16, v199
	v_mul_f32_e32 v161, v162, v161
	v_and_b32_e32 v162, 0xffff0000, v199
	v_mul_f32_e32 v162, v163, v162
	v_cvt_pk_bf16_f32 v161, v161, v162
	v_lshlrev_b64 v[162:163], 12, v[196:197]
	v_lshl_add_u64 v[162:163], v[194:195], 0, v[162:163]
	global_store_dwordx2 v[162:163], v[160:161], off
	s_barrier
	s_cbranch_scc0 .LBB0_1099

.LBB0_1126:
	s_nop 7
	v_cndmask_b32_e64 v160, v160, 0, s[54:55]
	v_cndmask_b32_e64 v161, 0, v161, s[56:57]
	v_cvt_pk_bf16_f32 v160, v160, v161
	v_cndmask_b32_e64 v161, v162, 0, s[58:59]
	v_cndmask_b32_e64 v162, v163, 0, s[60:61]
	v_cvt_pk_bf16_f32 v161, v161, v162
	v_cndmask_b32_e64 v160, 0, v160, s[44:45]
	v_cndmask_b32_e64 v161, 0, v161, s[44:45]
	v_add_u32_e32 v186, 0x1000, v230
	v_add_u32_e32 v187, 0x2000, v230
	v_add_u32_e32 v251, 0x3000, v230
	ds_write_b64 v229, v[160:161]
	v_cvt_pk_bf16_f32 v160, v84, v85
	v_cvt_pk_bf16_f32 v161, v86, v87
	v_cvt_pk_bf16_f32 v162, v72, v73
	v_cvt_pk_bf16_f32 v163, v74, v75
	ds_read2_b64 v[164:167], v230 offset1:4
	ds_read2_b64 v[168:171], v186 offset0:32 offset1:36
	ds_read2_b64 v[172:175], v187 offset0:64 offset1:68
	ds_read2_b64 v[176:179], v251 offset0:96 offset1:100
	ds_read2_b64 v[2:5], v230 offset0:8 offset1:12
	ds_read2_b64 v[6:9], v186 offset0:40 offset1:44
	ds_read2_b64 v[10:13], v187 offset0:72 offset1:76
	ds_read2_b64 v[14:17], v251 offset0:104 offset1:108
	ds_read2_b64 v[18:21], v230 offset0:16 offset1:20
	ds_read2_b64 v[22:25], v186 offset0:48 offset1:52
	ds_read2_b64 v[26:29], v187 offset0:80 offset1:84
	ds_read2_b64 v[30:33], v251 offset0:112 offset1:116
	ds_read2_b64 v[36:39], v230 offset0:24 offset1:28
	ds_read2_b64 v[40:43], v186 offset0:56 offset1:60
	ds_read2_b64 v[44:47], v187 offset0:88 offset1:92
	ds_read2_b64 v[48:51], v251 offset0:120 offset1:124
	s_waitcnt lgkmcnt(15)
	v_mfma_f32_16x16x32_bf16 v[164:167], v[160:163], v[164:167], 0
	s_andn2_b64 vcc, exec, s[16:17]
	s_waitcnt lgkmcnt(14)
	v_mfma_f32_16x16x32_bf16 v[168:171], v[160:163], v[168:171], 0
	s_waitcnt lgkmcnt(13)
	v_mfma_f32_16x16x32_bf16 v[172:175], v[160:163], v[172:175], 0
	s_waitcnt lgkmcnt(12)
	v_mfma_f32_16x16x32_bf16 v[160:163], v[160:163], v[176:179], 0
	v_cvt_pk_bf16_f32 v176, v76, v77
	v_cvt_pk_bf16_f32 v177, v78, v79
	v_cvt_pk_bf16_f32 v178, v80, v81
	v_cvt_pk_bf16_f32 v179, v82, v83
	s_nop 1
	s_waitcnt lgkmcnt(11)
	v_mfma_f32_16x16x32_bf16 v[164:167], v[176:179], v[2:5], v[164:167]
	s_waitcnt lgkmcnt(10)
	v_mfma_f32_16x16x32_bf16 v[168:171], v[176:179], v[6:9], v[168:171]
	s_waitcnt lgkmcnt(9)
	v_mfma_f32_16x16x32_bf16 v[172:175], v[176:179], v[10:13], v[172:175]
	s_waitcnt lgkmcnt(8)
	v_mfma_f32_16x16x32_bf16 v[160:163], v[176:179], v[14:17], v[160:163]
	v_cvt_pk_bf16_f32 v176, v132, v133
	v_cvt_pk_bf16_f32 v177, v134, v135
	v_cvt_pk_bf16_f32 v178, v100, v101
	v_cvt_pk_bf16_f32 v179, v102, v103
	s_nop 1
	s_waitcnt lgkmcnt(7)
	v_mfma_f32_16x16x32_bf16 v[164:167], v[176:179], v[18:21], v[164:167]
	s_waitcnt lgkmcnt(6)
	v_mfma_f32_16x16x32_bf16 v[168:171], v[176:179], v[22:25], v[168:171]
	s_waitcnt lgkmcnt(5)
	v_mfma_f32_16x16x32_bf16 v[172:175], v[176:179], v[26:29], v[172:175]
	s_waitcnt lgkmcnt(4)
	v_mfma_f32_16x16x32_bf16 v[160:163], v[176:179], v[30:33], v[160:163]
	v_cvt_pk_bf16_f32 v176, v108, v109
	v_cvt_pk_bf16_f32 v177, v110, v111
	v_cvt_pk_bf16_f32 v178, v128, v129
	v_cvt_pk_bf16_f32 v179, v130, v131
	s_nop 1
	s_waitcnt lgkmcnt(3)
	v_mfma_f32_16x16x32_bf16 v[164:167], v[176:179], v[36:39], v[164:167]
	s_waitcnt lgkmcnt(2)
	v_mfma_f32_16x16x32_bf16 v[168:171], v[176:179], v[40:43], v[168:171]
	s_waitcnt lgkmcnt(1)
	v_mfma_f32_16x16x32_bf16 v[186:189], v[176:179], v[44:47], v[172:175]
	s_waitcnt lgkmcnt(0)
	v_mfma_f32_16x16x32_bf16 v[160:163], v[176:179], v[48:51], v[160:163]
	s_barrier
	ds_read_b128 v[180:183], v231 offset:18432
	ds_read_b128 v[176:179], v232 offset:18432
	ds_read_b128 v[36:39], v233
	ds_read_b128 v[40:43], v233 offset:2304
	ds_read_b128 v[44:47], v233 offset:4608
	ds_read_b128 v[48:51], v233 offset:6912
	ds_read_b128 v[52:55], v233 offset:4672
	ds_read_b128 v[56:59], v233 offset:6976
	s_waitcnt lgkmcnt(5)
	v_mfma_f32_16x16x32_bf16 v[172:175], v[180:183], v[36:39], v[164:167]
	s_waitcnt lgkmcnt(4)
	v_mfma_f32_16x16x32_bf16 v[168:171], v[180:183], v[40:43], v[168:171]
	s_waitcnt lgkmcnt(3)
	v_mfma_f32_16x16x32_bf16 v[164:167], v[180:183], v[44:47], v[186:189]
	s_waitcnt lgkmcnt(2)
	v_mfma_f32_16x16x32_bf16 v[160:163], v[180:183], v[48:51], v[160:163]
	s_waitcnt lgkmcnt(1)
	v_mfma_f32_16x16x32_bf16 v[164:167], v[176:179], v[52:55], v[164:167]
	s_waitcnt lgkmcnt(0)
	v_mfma_f32_16x16x32_bf16 v[160:163], v[176:179], v[56:59], v[160:163]
	s_cbranch_vccnz .LBB0_1128
	ds_read_b128 v[36:39], v213
	ds_read_b128 v[40:43], v234
	ds_read_b128 v[44:47], v235
	ds_read_b128 v[48:51], v213 offset:64
	ds_read_b128 v[52:55], v236 offset:2304
	ds_read_b128 v[56:59], v237 offset:2304
	ds_read_b128 v[60:63], v213 offset:128
	ds_read_b128 v[64:67], v238 offset:4608
	ds_read_b128 v[186:189], v239 offset:4608
	s_waitcnt lgkmcnt(6)
	v_pk_mul_f32 v[86:87], v[86:87], v[38:39]
	v_pk_mul_f32 v[84:85], v[84:85], v[36:37]
	s_nop 1
	v_mfma_f32_16x16x32_bf16 v[84:87], v[40:43], v[180:183], v[84:87]
	v_mfma_f32_16x16x32_bf16 v[84:87], v[44:47], v[176:179], v[84:87]
	ds_read_b128 v[36:39], v213 offset:192
	ds_read_b128 v[40:43], v240 offset:6912
	ds_read_b128 v[44:47], v241 offset:6912
	s_waitcnt lgkmcnt(6)
	v_pk_mul_f32 v[74:75], v[74:75], v[50:51]
	v_pk_mul_f32 v[72:73], v[72:73], v[48:49]
	s_nop 1
	v_mfma_f32_16x16x32_bf16 v[72:75], v[52:55], v[180:183], v[72:75]
	v_mfma_f32_16x16x32_bf16 v[72:75], v[56:59], v[176:179], v[72:75]
	ds_read_b128 v[48:51], v213 offset:256
	ds_read_b128 v[52:55], v234 offset:9216
	ds_read_b128 v[56:59], v235 offset:9216
	s_waitcnt lgkmcnt(6)
	v_pk_mul_f32 v[78:79], v[78:79], v[62:63]
	v_pk_mul_f32 v[76:77], v[76:77], v[60:61]
	s_nop 1
	v_mfma_f32_16x16x32_bf16 v[76:79], v[64:67], v[180:183], v[76:79]
	v_mfma_f32_16x16x32_bf16 v[76:79], v[186:189], v[176:179], v[76:79]
	ds_read_b128 v[60:63], v213 offset:320
	ds_read_b128 v[64:67], v236 offset:11520
	ds_read_b128 v[186:189], v237 offset:11520
	s_waitcnt lgkmcnt(6)
	v_pk_mul_f32 v[82:83], v[82:83], v[38:39]
	v_pk_mul_f32 v[80:81], v[80:81], v[36:37]
	s_nop 1
	v_mfma_f32_16x16x32_bf16 v[80:83], v[40:43], v[180:183], v[80:83]
	v_mfma_f32_16x16x32_bf16 v[80:83], v[44:47], v[176:179], v[80:83]
	ds_read_b128 v[36:39], v213 offset:384
	ds_read_b128 v[40:43], v238 offset:13824
	ds_read_b128 v[44:47], v239 offset:13824
	s_waitcnt lgkmcnt(6)
	v_pk_mul_f32 v[134:135], v[134:135], v[50:51]
	v_pk_mul_f32 v[132:133], v[132:133], v[48:49]
	s_nop 1
	v_mfma_f32_16x16x32_bf16 v[132:135], v[52:55], v[180:183], v[132:135]
	v_mfma_f32_16x16x32_bf16 v[132:135], v[56:59], v[176:179], v[132:135]
	ds_read_b128 v[48:51], v213 offset:448
	ds_read_b128 v[52:55], v240 offset:16128
	ds_read_b128 v[56:59], v241 offset:16128
	s_waitcnt lgkmcnt(6)
	v_pk_mul_f32 v[102:103], v[102:103], v[62:63]
	v_pk_mul_f32 v[100:101], v[100:101], v[60:61]
	s_nop 1
	v_mfma_f32_16x16x32_bf16 v[100:103], v[64:67], v[180:183], v[100:103]
	v_mfma_f32_16x16x32_bf16 v[100:103], v[186:189], v[176:179], v[100:103]
	s_waitcnt lgkmcnt(3)
	v_pk_mul_f32 v[110:111], v[110:111], v[38:39]
	v_pk_mul_f32 v[108:109], v[108:109], v[36:37]
	s_nop 1
	v_mfma_f32_16x16x32_bf16 v[108:111], v[40:43], v[180:183], v[108:111]
	v_mfma_f32_16x16x32_bf16 v[108:111], v[44:47], v[176:179], v[108:111]
	s_waitcnt lgkmcnt(0)
	v_pk_mul_f32 v[130:131], v[130:131], v[50:51]
	v_pk_mul_f32 v[128:129], v[128:129], v[48:49]
	s_nop 1
	v_mfma_f32_16x16x32_bf16 v[128:131], v[52:55], v[180:183], v[128:131]
	v_mfma_f32_16x16x32_bf16 v[128:131], v[56:59], v[176:179], v[128:131]

.LBB0_1336:
	v_add_co_u32_e32 v184, vcc, 0xff600000, v22
	s_nop 1
	v_addc_co_u32_e32 v185, vcc, -1, v23, vcc
	global_load_dwordx2 v[184:185], v[184:185], off
	v_add_co_u32_e32 v186, vcc, 0xff800000, v22
	s_nop 1
	v_addc_co_u32_e32 v187, vcc, -1, v23, vcc
	global_load_dwordx2 v[186:187], v[186:187], off
	v_add_co_u32_e32 v188, vcc, 0xffa00000, v22
	s_nop 1
	v_addc_co_u32_e32 v189, vcc, -1, v23, vcc
	global_load_dwordx2 v[188:189], v[188:189], off
	v_add_co_u32_e32 v190, vcc, 0xffc00000, v22
	s_nop 1
	v_addc_co_u32_e32 v191, vcc, -1, v23, vcc
	global_load_dwordx2 v[190:191], v[190:191], off
	v_add_co_u32_e32 v192, vcc, 0xffe00000, v22
	s_nop 1
	v_addc_co_u32_e32 v193, vcc, -1, v23, vcc
	global_load_dwordx2 v[192:193], v[192:193], off
	global_load_dwordx2 v[194:195], v[22:23], off
	v_add_co_u32_e32 v28, vcc, 0xff200000, v22
	s_mov_b32 s0, 0xff400000
	s_nop 0
	v_addc_co_u32_e32 v29, vcc, -1, v23, vcc
	v_add_co_u32_e32 v36, vcc, s0, v22
	global_load_dwordx2 v[28:29], v[28:29], off
	s_nop 0
	v_addc_co_u32_e32 v37, vcc, -1, v23, vcc
	global_load_dwordx2 v[36:37], v[36:37], off
	v_lshl_add_u64 v[26:27], s[6:7], 1, v[16:17]
	s_mov_b32 s0, 0x200000
	global_load_dwordx2 v[32:33], v[26:27], off
	v_readlane_b32 s16, v252, 31
	v_readlane_b32 s17, v252, 32
	s_waitcnt vmcnt(0)
	v_cvt_f32_f16_e32 v30, v28
	v_cvt_f32_f16_sdwa v31, v28 dst_sel:DWORD dst_unused:UNUSED_PAD src0_sel:WORD_1
	v_cvt_f32_f16_e32 v28, v29
	v_cvt_f32_f16_sdwa v29, v29 dst_sel:DWORD dst_unused:UNUSED_PAD src0_sel:WORD_1
	v_cvt_f32_f16_e32 v38, v37
	v_cvt_f32_f16_sdwa v39, v37 dst_sel:DWORD dst_unused:UNUSED_PAD src0_sel:WORD_1
	v_cvt_f32_f16_e32 v40, v36
	v_cvt_f32_f16_sdwa v41, v36 dst_sel:DWORD dst_unused:UNUSED_PAD src0_sel:WORD_1
	v_add_co_u32_e32 v36, vcc, s0, v26
	v_pk_add_f32 v[28:29], v[28:29], 0 op_sel_hi:[1,0]
	s_nop 0
	v_addc_co_u32_e32 v37, vcc, 0, v27, vcc
	s_mov_b32 s0, 0xff600000
	v_pk_add_f32 v[28:29], v[28:29], v[38:39]
	v_add_co_u32_e32 v38, vcc, s0, v22
	v_pk_add_f32 v[30:31], v[30:31], 0 op_sel_hi:[1,0]
	s_nop 0
	v_addc_co_u32_e32 v39, vcc, -1, v23, vcc
	v_mov_b32_e32 v38, v184
	v_mov_b32_e32 v39, v185
	v_pk_add_f32 v[30:31], v[30:31], v[40:41]
	s_mov_b32 s0, 0x400000
	global_load_dwordx2 v[36:37], v[36:37], off
	v_cvt_f32_f16_e32 v40, v38
	v_cvt_f32_f16_sdwa v41, v38 dst_sel:DWORD dst_unused:UNUSED_PAD src0_sel:WORD_1
	v_cvt_f32_f16_e32 v38, v39
	v_cvt_f32_f16_sdwa v39, v39 dst_sel:DWORD dst_unused:UNUSED_PAD src0_sel:WORD_1
	v_pk_add_f32 v[30:31], v[30:31], v[40:41]
	v_pk_add_f32 v[28:29], v[28:29], v[38:39]
	v_add_co_u32_e32 v38, vcc, s0, v26
	s_mov_b32 s0, 0xff800000
	s_nop 0
	v_addc_co_u32_e32 v39, vcc, 0, v27, vcc
	v_add_co_u32_e32 v40, vcc, s0, v22
	s_mov_b32 s0, 0x600000
	s_nop 0
	v_addc_co_u32_e32 v41, vcc, -1, v23, vcc
	v_mov_b32_e32 v40, v186
	v_mov_b32_e32 v41, v187
	v_cvt_f32_f16_e32 v42, v41
	v_cvt_f32_f16_sdwa v43, v41 dst_sel:DWORD dst_unused:UNUSED_PAD src0_sel:WORD_1
	v_cvt_f32_f16_e32 v44, v40
	v_cvt_f32_f16_sdwa v45, v40 dst_sel:DWORD dst_unused:UNUSED_PAD src0_sel:WORD_1
	v_add_co_u32_e32 v40, vcc, s0, v26
	s_mov_b32 s0, 0xffa00000
	s_nop 0
	v_addc_co_u32_e32 v41, vcc, 0, v27, vcc
	v_pk_add_f32 v[28:29], v[28:29], v[42:43]
	v_add_co_u32_e32 v42, vcc, s0, v22
	v_pk_add_f32 v[30:31], v[30:31], v[44:45]
	s_nop 0
	v_addc_co_u32_e32 v43, vcc, -1, v23, vcc
	v_mov_b32_e32 v42, v188
	v_mov_b32_e32 v43, v189
	s_mov_b32 s0, 0x800000
	global_load_dwordx2 v[38:39], v[38:39], off
	v_cvt_f32_f16_e32 v44, v42
	v_cvt_f32_f16_sdwa v45, v42 dst_sel:DWORD dst_unused:UNUSED_PAD src0_sel:WORD_1
	v_cvt_f32_f16_e32 v42, v43
	v_cvt_f32_f16_sdwa v43, v43 dst_sel:DWORD dst_unused:UNUSED_PAD src0_sel:WORD_1
	global_load_dwordx2 v[40:41], v[40:41], off
	v_pk_add_f32 v[30:31], v[30:31], v[44:45]
	v_pk_add_f32 v[28:29], v[28:29], v[42:43]
	v_add_co_u32_e32 v42, vcc, s0, v26
	s_mov_b32 s0, 0xffc00000
	s_nop 0
	v_addc_co_u32_e32 v43, vcc, 0, v27, vcc
	v_add_co_u32_e32 v44, vcc, s0, v22
	s_mov_b32 s0, 0xa00000
	s_nop 0
	v_addc_co_u32_e32 v45, vcc, -1, v23, vcc
	v_mov_b32_e32 v44, v190
	v_mov_b32_e32 v45, v191
	v_cvt_f32_f16_e32 v46, v45
	v_cvt_f32_f16_sdwa v47, v45 dst_sel:DWORD dst_unused:UNUSED_PAD src0_sel:WORD_1
	v_cvt_f32_f16_e32 v48, v44
	v_cvt_f32_f16_sdwa v49, v44 dst_sel:DWORD dst_unused:UNUSED_PAD src0_sel:WORD_1
	v_add_co_u32_e32 v44, vcc, s0, v26
	s_mov_b32 s0, 0xffe00000
	s_nop 0
	v_addc_co_u32_e32 v45, vcc, 0, v27, vcc
	v_pk_add_f32 v[28:29], v[28:29], v[46:47]
	v_add_co_u32_e32 v46, vcc, s0, v22
	v_pk_add_f32 v[30:31], v[30:31], v[48:49]
	s_nop 0
	v_addc_co_u32_e32 v47, vcc, -1, v23, vcc
	v_mov_b32_e32 v46, v192
	v_mov_b32_e32 v47, v193
	s_mov_b32 s0, 0xc00000
	global_load_dwordx2 v[42:43], v[42:43], off
	v_cvt_f32_f16_e32 v48, v46
	v_cvt_f32_f16_sdwa v49, v46 dst_sel:DWORD dst_unused:UNUSED_PAD src0_sel:WORD_1
	v_cvt_f32_f16_e32 v46, v47
	v_cvt_f32_f16_sdwa v47, v47 dst_sel:DWORD dst_unused:UNUSED_PAD src0_sel:WORD_1
	global_load_dwordx2 v[44:45], v[44:45], off
	v_pk_add_f32 v[30:31], v[30:31], v[48:49]
	v_pk_add_f32 v[28:29], v[28:29], v[46:47]
	v_add_co_u32_e32 v46, vcc, s0, v26
	s_mov_b32 s0, 0xe00000
	s_nop 0
	v_addc_co_u32_e32 v47, vcc, 0, v27, vcc
	global_load_dwordx2 v[46:47], v[46:47], off
	s_nop 0
	v_mov_b32_e32 v48, v194
	v_mov_b32_e32 v49, v195
	v_add_co_u32_e32 v26, vcc, s0, v26
	s_ashr_i32 s0, s13, 4
	s_and_b32 s0, s0, -4
	s_add_i32 s0, s0, s4
	s_mul_hi_i32 s1, s0, 0xc000
	s_mul_i32 s0, s0, 0xc000
	s_add_u32 s0, s16, s0
	v_addc_co_u32_e32 v27, vcc, 0, v27, vcc
	s_addc_u32 s1, s17, s1
	s_waitcnt vmcnt(0)
	v_cvt_f32_f16_sdwa v57, v49 dst_sel:DWORD dst_unused:UNUSED_PAD src0_sel:WORD_1
	v_cvt_f32_f16_e32 v56, v49
	v_cvt_f32_f16_sdwa v59, v48 dst_sel:DWORD dst_unused:UNUSED_PAD src0_sel:WORD_1
	v_cvt_f32_f16_e32 v58, v48
	global_load_dwordx2 v[48:49], v[26:27], off
	v_lshl_add_u64 v[26:27], v[10:11], 4, s[0:1]
	v_pk_add_f32 v[28:29], v[28:29], v[56:57]
	v_add_co_u32_e32 v56, vcc, s72, v26
	v_pk_add_f32 v[30:31], v[30:31], v[58:59]
	s_nop 0
	v_addc_co_u32_e32 v57, vcc, 0, v27, vcc
	global_load_dwordx4 v[56:59], v[56:57], off
	s_add_i32 s0, s13, 0x2000
	s_ashr_i32 s1, s0, 31
	s_lshl_b64 s[6:7], s[0:1], 12
	s_andn2_b64 vcc, exec, s[10:11]
	s_waitcnt vmcnt(0)
	v_pk_fma_f32 v[28:29], v[28:29], v[58:59], v[8:9]
	v_pk_fma_f32 v[30:31], v[30:31], v[56:57], v[6:7]
	v_lshl_add_u64 v[6:7], v[18:19], 0, s[6:7]
	v_cvt_pk_f16_f32 v9, v28, v29
	v_cvt_pk_f16_f32 v8, v30, v31
	global_store_dwordx2 v[6:7], v[8:9], off
	v_cndmask_b32_e64 v6, 0, 1, s[10:11]
	v_cmp_ne_u32_e64 s[42:43], 1, v6
	s_cbranch_vccnz .LBB0_1338
	v_cvt_f32_f16_sdwa v9, v33 dst_sel:DWORD dst_unused:UNUSED_PAD src0_sel:WORD_1
	v_cvt_f32_f16_e32 v8, v33
	v_cvt_f32_f16_sdwa v7, v32 dst_sel:DWORD dst_unused:UNUSED_PAD src0_sel:WORD_1
	v_cvt_f32_f16_e32 v6, v32
	v_cvt_f32_f16_sdwa v33, v37 dst_sel:DWORD dst_unused:UNUSED_PAD src0_sel:WORD_1
	v_cvt_f32_f16_e32 v32, v37
	v_cvt_f32_f16_sdwa v57, v36 dst_sel:DWORD dst_unused:UNUSED_PAD src0_sel:WORD_1
	v_cvt_f32_f16_e32 v56, v36
	v_cvt_f32_f16_sdwa v37, v39 dst_sel:DWORD dst_unused:UNUSED_PAD src0_sel:WORD_1
	v_cvt_f32_f16_e32 v36, v39
	v_pk_add_f32 v[8:9], v[8:9], 0 op_sel_hi:[1,0]
	v_pk_add_f32 v[6:7], v[6:7], 0 op_sel_hi:[1,0]
	v_pk_add_f32 v[8:9], v[8:9], v[32:33]
	v_cvt_f32_f16_sdwa v33, v38 dst_sel:DWORD dst_unused:UNUSED_PAD src0_sel:WORD_1
	v_cvt_f32_f16_e32 v32, v38
	v_pk_add_f32 v[8:9], v[8:9], v[36:37]
	v_cvt_f32_f16_sdwa v37, v40 dst_sel:DWORD dst_unused:UNUSED_PAD src0_sel:WORD_1
	v_cvt_f32_f16_e32 v36, v40
	v_pk_add_f32 v[6:7], v[6:7], v[56:57]
	s_ashr_i32 s0, s14, 4
	v_pk_add_f32 v[6:7], v[6:7], v[32:33]
	v_cvt_f32_f16_sdwa v33, v41 dst_sel:DWORD dst_unused:UNUSED_PAD src0_sel:WORD_1
	v_cvt_f32_f16_e32 v32, v41
	v_pk_add_f32 v[6:7], v[6:7], v[36:37]
	v_cvt_f32_f16_sdwa v37, v43 dst_sel:DWORD dst_unused:UNUSED_PAD src0_sel:WORD_1
	v_cvt_f32_f16_e32 v36, v43
	v_pk_add_f32 v[8:9], v[8:9], v[32:33]
	v_cvt_f32_f16_sdwa v33, v42 dst_sel:DWORD dst_unused:UNUSED_PAD src0_sel:WORD_1
	v_cvt_f32_f16_e32 v32, v42
	v_pk_add_f32 v[8:9], v[8:9], v[36:37]
	v_cvt_f32_f16_sdwa v37, v44 dst_sel:DWORD dst_unused:UNUSED_PAD src0_sel:WORD_1
	v_cvt_f32_f16_e32 v36, v44
	v_pk_add_f32 v[6:7], v[6:7], v[32:33]
	v_cvt_f32_f16_sdwa v33, v45 dst_sel:DWORD dst_unused:UNUSED_PAD src0_sel:WORD_1
	v_cvt_f32_f16_e32 v32, v45
	v_pk_add_f32 v[6:7], v[6:7], v[36:37]
	v_cvt_f32_f16_sdwa v37, v47 dst_sel:DWORD dst_unused:UNUSED_PAD src0_sel:WORD_1
	v_cvt_f32_f16_e32 v36, v47
	v_pk_add_f32 v[8:9], v[8:9], v[32:33]
	v_cvt_f32_f16_sdwa v33, v46 dst_sel:DWORD dst_unused:UNUSED_PAD src0_sel:WORD_1
	v_cvt_f32_f16_e32 v32, v46
	s_and_b32 s0, s0, -4
	v_pk_add_f32 v[8:9], v[8:9], v[36:37]
	v_cvt_f32_f16_sdwa v37, v48 dst_sel:DWORD dst_unused:UNUSED_PAD src0_sel:WORD_1
	v_cvt_f32_f16_e32 v36, v48
	s_add_i32 s0, s0, s4
	s_mul_hi_i32 s1, s0, 0xc000
	s_mul_i32 s0, s0, 0xc000
	s_add_u32 s0, s16, s0
	v_pk_add_f32 v[6:7], v[6:7], v[32:33]
	v_cvt_f32_f16_sdwa v33, v49 dst_sel:DWORD dst_unused:UNUSED_PAD src0_sel:WORD_1
	v_cvt_f32_f16_e32 v32, v49
	s_addc_u32 s1, s17, s1
	v_pk_add_f32 v[36:37], v[6:7], v[36:37]
	v_lshl_add_u64 v[6:7], v[10:11], 4, s[0:1]
	v_add_co_u32_e32 v6, vcc, s72, v6
	v_pk_add_f32 v[32:33], v[8:9], v[32:33]
	s_nop 0
	v_addc_co_u32_e32 v7, vcc, 0, v7, vcc
	global_load_dwordx4 v[6:9], v[6:7], off
	s_add_i32 s0, s14, 0x2000
	s_ashr_i32 s1, s0, 31
	s_lshl_b64 s[0:1], s[0:1], 12
	s_waitcnt vmcnt(0)
	v_pk_fma_f32 v[4:5], v[32:33], v[8:9], v[4:5]
	v_pk_fma_f32 v[2:3], v[36:37], v[6:7], v[2:3]
	v_lshl_add_u64 v[6:7], v[18:19], 0, s[0:1]
	v_cvt_pk_f16_f32 v9, v4, v5
	v_cvt_pk_f16_f32 v8, v2, v3
	global_store_dwordx2 v[6:7], v[8:9], off
